# prep transpose loops (w_in, sample V^T caches): next tile's global load prefetched, 2-way unrolled; uvscan item order rebalanced
# speedup vs baseline: 1.0548x; 1.0060x over previous
.LBB0_742:
	s_and_b32 s0, s51, 0x3c0
	s_and_b32 s46, s50, 0xffffffe0
	v_add_u32_e32 v110, s0, v11
	v_mov_b64_e32 v[108:109], s[40:41]
	s_movk_i32 s47, 0x6e80
	v_mad_i64_i32 v[108:109], s[48:49], v110, s47, v[108:109]
	s_ashr_i32 s47, s46, 31
	v_lshl_add_u64 v[108:109], s[46:47], 2, v[108:109]
	v_lshl_add_u64 v[108:109], v[108:109], 0, v[0:1]
	global_load_dwordx4 v[100:103], v[108:109], off
.Lpf0_topP:
	s_and_b32 s0, s51, 0x3c0
	s_and_b32 s46, s50, 0xffffffe0
	s_movk_i32 s47, 0x6e80
	s_ashr_i32 s47, s46, 31
	v_readlane_b32 s71, v253, 7
	v_readlane_b32 s72, v253, 50
	v_readlane_b32 s70, v253, 20
	s_add_i32 s71, s51, s71
	s_add_i32 s72, s52, s72
	s_add_i32 s70, s50, s70
	s_cmpk_gt_i32 s72, 0xdcf
	s_cbranch_scc1 .Lpf0_nopfP
	s_and_b32 s64, s71, 0x3c0
	s_and_b32 s66, s70, 0xffffffe0
	v_add_u32_e32 v110, s64, v11
	v_mov_b64_e32 v[108:109], s[40:41]
	s_movk_i32 s67, 0x6e80
	v_mad_i64_i32 v[108:109], s[68:69], v110, s67, v[108:109]
	s_ashr_i32 s67, s66, 31
	v_lshl_add_u64 v[108:109], s[66:67], 2, v[108:109]
	v_lshl_add_u64 v[108:109], v[108:109], 0, v[0:1]
	global_load_dwordx4 v[104:107], v[108:109], off
	s_waitcnt vmcnt(1)
	s_branch .Lpf0_goP

.Lpf0_goP:
	v_cvt_pk_bf16_f32 v2, v100, s0
	v_cvt_pk_bf16_f32 v3, v101, s0
	v_cvt_pk_bf16_f32 v4, v102, s0
	v_cvt_pk_bf16_f32 v5, v103, s0
	ds_write_b16 v12, v2
	ds_write_b16 v12, v3 offset:144
	ds_write_b16 v12, v4 offset:288
	ds_write_b16 v12, v5 offset:432
	s_waitcnt lgkmcnt(0)
	s_barrier
	s_and_saveexec_b64 s[48:49], s[4:5]
	s_cbranch_execz .Lpf0_latchP
	s_add_i32 s47, s46, 0x60
	s_cmpk_lt_i32 s46, 0x1a0
	s_cselect_b32 s46, s46, s47
	v_add_u32_e32 v6, s46, v11
	ds_read_b128 v[2:5], v14
	v_ashrrev_i32_e32 v7, 31, v6
	v_lshlrev_b64 v[6:7], 11, v[6:7]
	v_lshl_add_u64 v[6:7], s[44:45], 0, v[6:7]
	s_lshl_b32 s0, s0, 1
	v_lshl_add_u64 v[6:7], v[6:7], 0, s[0:1]
	v_lshlrev_b32_e32 v8, 1, v13
	v_mov_b32_e32 v9, v1
	v_lshl_add_u64 v[6:7], v[6:7], 0, v[8:9]
	s_waitcnt lgkmcnt(0)
	global_store_dwordx4 v[6:7], v[2:5], off
.Lpf0_latchP:
	s_or_b64 exec, exec, s[48:49]
	s_mov_b32 s51, s71
	s_mov_b32 s52, s72
	s_mov_b32 s50, s70
	s_cmpk_gt_i32 s52, 0xdcf
	s_barrier
	v_readlane_b32 s47, v253, 51
	s_cbranch_scc1 .LBB0_744
.Lpf0_topQ:
	s_and_b32 s0, s51, 0x3c0
	s_and_b32 s46, s50, 0xffffffe0
	s_movk_i32 s47, 0x6e80
	s_ashr_i32 s47, s46, 31
	v_readlane_b32 s71, v253, 7
	v_readlane_b32 s72, v253, 50
	v_readlane_b32 s70, v253, 20
	s_add_i32 s71, s51, s71
	s_add_i32 s72, s52, s72
	s_add_i32 s70, s50, s70
	s_cmpk_gt_i32 s72, 0xdcf
	s_cbranch_scc1 .Lpf0_nopfQ
	s_and_b32 s64, s71, 0x3c0
	s_and_b32 s66, s70, 0xffffffe0
	v_add_u32_e32 v110, s64, v11
	v_mov_b64_e32 v[108:109], s[40:41]
	s_movk_i32 s67, 0x6e80
	v_mad_i64_i32 v[108:109], s[68:69], v110, s67, v[108:109]
	s_ashr_i32 s67, s66, 31
	v_lshl_add_u64 v[108:109], s[66:67], 2, v[108:109]
	v_lshl_add_u64 v[108:109], v[108:109], 0, v[0:1]
	global_load_dwordx4 v[100:103], v[108:109], off
	s_waitcnt vmcnt(1)
	s_branch .Lpf0_goQ

.Lpf0_goQ:
	v_cvt_pk_bf16_f32 v2, v104, s0
	v_cvt_pk_bf16_f32 v3, v105, s0
	v_cvt_pk_bf16_f32 v4, v106, s0
	v_cvt_pk_bf16_f32 v5, v107, s0
	ds_write_b16 v12, v2
	ds_write_b16 v12, v3 offset:144
	ds_write_b16 v12, v4 offset:288
	ds_write_b16 v12, v5 offset:432
	s_waitcnt lgkmcnt(0)
	s_barrier
	s_and_saveexec_b64 s[48:49], s[4:5]
	s_cbranch_execz .Lpf0_latchQ
	s_add_i32 s47, s46, 0x60
	s_cmpk_lt_i32 s46, 0x1a0
	s_cselect_b32 s46, s46, s47
	v_add_u32_e32 v6, s46, v11
	ds_read_b128 v[2:5], v14
	v_ashrrev_i32_e32 v7, 31, v6
	v_lshlrev_b64 v[6:7], 11, v[6:7]
	v_lshl_add_u64 v[6:7], s[44:45], 0, v[6:7]
	s_lshl_b32 s0, s0, 1
	v_lshl_add_u64 v[6:7], v[6:7], 0, s[0:1]
	v_lshlrev_b32_e32 v8, 1, v13
	v_mov_b32_e32 v9, v1
	v_lshl_add_u64 v[6:7], v[6:7], 0, v[8:9]
	s_waitcnt lgkmcnt(0)
	global_store_dwordx4 v[6:7], v[2:5], off
.Lpf0_latchQ:
	s_or_b64 exec, exec, s[48:49]
	s_mov_b32 s51, s71
	s_mov_b32 s52, s72
	s_mov_b32 s50, s70
	s_cmpk_gt_i32 s52, 0xdcf
	s_barrier
	v_readlane_b32 s47, v253, 51
	s_cbranch_scc1 .LBB0_744
	s_branch .Lpf0_topP

.LBB0_768:
	s_ashr_i32 s6, s49, 7
	s_ashr_i32 s7, s6, 31
	s_and_b32 s50, s49, 0x60
	s_lshl_b64 s[24:25], s[6:7], 20
	s_add_u32 s24, s46, s24
	s_addc_u32 s25, s47, s25
	s_and_b32 s7, s48, 0x7c0
	v_add_u32_e32 v108, s7, v11
	v_ashrrev_i32_e32 v109, 31, v108
	v_lshlrev_b64 v[108:109], 9, v[108:109]
	v_lshl_add_u64 v[108:109], s[24:25], 0, v[108:109]
	s_lshl_b32 s0, s50, 2
	v_lshl_add_u64 v[108:109], v[108:109], 0, s[0:1]
	v_lshl_add_u64 v[108:109], v[108:109], 0, v[0:1]
	global_load_dwordx4 v[100:103], v[108:109], off
.Lpf2_topP:
	s_ashr_i32 s6, s49, 7
	s_ashr_i32 s7, s6, 31
	s_and_b32 s50, s49, 0x60
	s_lshl_b64 s[24:25], s[6:7], 20
	s_add_u32 s24, s46, s24
	s_addc_u32 s25, s47, s25
	s_and_b32 s7, s48, 0x7c0
	s_lshl_b32 s0, s50, 2
	v_readlane_b32 s91, v253, 50
	v_readlane_b32 s90, v253, 7
	s_add_i32 s91, s49, s91
	s_add_i32 s90, s48, s90
	s_cmpk_gt_i32 s91, 0x3ff
	s_cbranch_scc1 .Lpf2_nopfP
	s_mov_b32 s85, s1
	s_ashr_i32 s86, s91, 7
	s_ashr_i32 s87, s86, 31
	s_and_b32 s92, s91, 0x60
	s_lshl_b64 s[88:89], s[86:87], 20
	s_add_u32 s88, s46, s88
	s_addc_u32 s89, s47, s89
	s_and_b32 s87, s90, 0x7c0
	v_add_u32_e32 v108, s87, v11
	v_ashrrev_i32_e32 v109, 31, v108
	v_lshlrev_b64 v[108:109], 9, v[108:109]
	v_lshl_add_u64 v[108:109], s[88:89], 0, v[108:109]
	s_lshl_b32 s84, s92, 2
	v_lshl_add_u64 v[108:109], v[108:109], 0, s[84:85]
	v_lshl_add_u64 v[108:109], v[108:109], 0, v[0:1]
	global_load_dwordx4 v[104:107], v[108:109], off
	s_waitcnt vmcnt(1)
	s_branch .Lpf2_goP

.Lpf2_goP:
	v_cvt_pk_bf16_f32 v4, v100, s0
	v_cvt_pk_bf16_f32 v5, v101, s0
	v_cvt_pk_bf16_f32 v6, v102, s0
	v_cvt_pk_bf16_f32 v7, v103, s0
	ds_write_b16 v12, v4
	ds_write_b16 v12, v5 offset:144
	ds_write_b16 v12, v6 offset:288
	ds_write_b16 v12, v7 offset:432
	s_waitcnt lgkmcnt(0)
	s_barrier
	s_and_saveexec_b64 s[24:25], s[4:5]
	s_cbranch_execz .Lpf2_latchP
	s_mul_hi_i32 s0, s6, 0x84000
	s_mul_i32 s6, s6, 0x84000
	s_add_u32 s52, s26, s6
	s_addc_u32 s53, s27, s0
	ds_read_b128 v[4:7], v14
	v_add_u32_e32 v10, s50, v11
	v_mov_b64_e32 v[8:9], s[52:53]
	s_movk_i32 s0, 0x1080
	v_mad_i64_i32 v[8:9], s[50:51], v10, s0, v[8:9]
	v_or_b32_e32 v10, s7, v13
	s_movk_i32 s0, 0x7f0
	v_and_or_b32 v15, v10, s0, v2
	v_lshlrev_b32_e32 v16, 1, v15
	v_mov_b32_e32 v17, v1
	v_lshl_add_u64 v[16:17], v[8:9], 0, v[16:17]
	s_waitcnt lgkmcnt(0)
	global_store_dwordx2 v[16:17], v[4:5], off
	v_or_b32_e32 v4, v10, v3
	v_lshlrev_b32_e32 v4, 1, v4
	v_mov_b32_e32 v5, v1
	v_lshl_add_u64 v[4:5], v[8:9], 0, v[4:5]
	global_store_dwordx2 v[4:5], v[6:7], off
.Lpf2_latchP:
	s_or_b64 exec, exec, s[24:25]
	s_mov_b32 s49, s91
	s_mov_b32 s48, s90
	s_cmpk_gt_i32 s49, 0x3ff
	s_barrier
	v_readlane_b32 s7, v253, 51
	s_cbranch_scc1 .LBB0_770
.Lpf2_topQ:
	s_ashr_i32 s6, s49, 7
	s_ashr_i32 s7, s6, 31
	s_and_b32 s50, s49, 0x60
	s_lshl_b64 s[24:25], s[6:7], 20
	s_add_u32 s24, s46, s24
	s_addc_u32 s25, s47, s25
	s_and_b32 s7, s48, 0x7c0
	s_lshl_b32 s0, s50, 2
	v_readlane_b32 s91, v253, 50
	v_readlane_b32 s90, v253, 7
	s_add_i32 s91, s49, s91
	s_add_i32 s90, s48, s90
	s_cmpk_gt_i32 s91, 0x3ff
	s_cbranch_scc1 .Lpf2_nopfQ
	s_mov_b32 s85, s1
	s_ashr_i32 s86, s91, 7
	s_ashr_i32 s87, s86, 31
	s_and_b32 s92, s91, 0x60
	s_lshl_b64 s[88:89], s[86:87], 20
	s_add_u32 s88, s46, s88
	s_addc_u32 s89, s47, s89
	s_and_b32 s87, s90, 0x7c0
	v_add_u32_e32 v108, s87, v11
	v_ashrrev_i32_e32 v109, 31, v108
	v_lshlrev_b64 v[108:109], 9, v[108:109]
	v_lshl_add_u64 v[108:109], s[88:89], 0, v[108:109]
	s_lshl_b32 s84, s92, 2
	v_lshl_add_u64 v[108:109], v[108:109], 0, s[84:85]
	v_lshl_add_u64 v[108:109], v[108:109], 0, v[0:1]
	global_load_dwordx4 v[100:103], v[108:109], off
	s_waitcnt vmcnt(1)
	s_branch .Lpf2_goQ

.Lpf2_goQ:
	v_cvt_pk_bf16_f32 v4, v104, s0
	v_cvt_pk_bf16_f32 v5, v105, s0
	v_cvt_pk_bf16_f32 v6, v106, s0
	v_cvt_pk_bf16_f32 v7, v107, s0
	ds_write_b16 v12, v4
	ds_write_b16 v12, v5 offset:144
	ds_write_b16 v12, v6 offset:288
	ds_write_b16 v12, v7 offset:432
	s_waitcnt lgkmcnt(0)
	s_barrier
	s_and_saveexec_b64 s[24:25], s[4:5]
	s_cbranch_execz .Lpf2_latchQ
	s_mul_hi_i32 s0, s6, 0x84000
	s_mul_i32 s6, s6, 0x84000
	s_add_u32 s52, s26, s6
	s_addc_u32 s53, s27, s0
	ds_read_b128 v[4:7], v14
	v_add_u32_e32 v10, s50, v11
	v_mov_b64_e32 v[8:9], s[52:53]
	s_movk_i32 s0, 0x1080
	v_mad_i64_i32 v[8:9], s[50:51], v10, s0, v[8:9]
	v_or_b32_e32 v10, s7, v13
	s_movk_i32 s0, 0x7f0
	v_and_or_b32 v15, v10, s0, v2
	v_lshlrev_b32_e32 v16, 1, v15
	v_mov_b32_e32 v17, v1
	v_lshl_add_u64 v[16:17], v[8:9], 0, v[16:17]
	s_waitcnt lgkmcnt(0)
	global_store_dwordx2 v[16:17], v[4:5], off
	v_or_b32_e32 v4, v10, v3
	v_lshlrev_b32_e32 v4, 1, v4
	v_mov_b32_e32 v5, v1
	v_lshl_add_u64 v[4:5], v[8:9], 0, v[4:5]
	global_store_dwordx2 v[4:5], v[6:7], off
.Lpf2_latchQ:
	s_or_b64 exec, exec, s[24:25]
	s_mov_b32 s49, s91
	s_mov_b32 s48, s90
	s_cmpk_gt_i32 s49, 0x3ff
	s_barrier
	v_readlane_b32 s7, v253, 51
	s_cbranch_scc1 .LBB0_770
	s_branch .Lpf2_topP

.LBB0_773:
	s_ashr_i32 s14, s51, 9
	s_ashr_i32 s15, s14, 31
	s_and_b32 s52, s51, 0x1e0
	s_lshl_b64 s[46:47], s[14:15], 22
	s_add_u32 s46, s48, s46
	s_addc_u32 s47, s49, s47
	s_and_b32 s15, s50, 0x7c0
	v_add_u32_e32 v108, s15, v11
	v_ashrrev_i32_e32 v109, 31, v108
	v_lshlrev_b64 v[108:109], 11, v[108:109]
	v_lshl_add_u64 v[108:109], s[46:47], 0, v[108:109]
	s_lshl_b32 s0, s52, 2
	v_lshl_add_u64 v[108:109], v[108:109], 0, s[0:1]
	v_lshl_add_u64 v[108:109], v[108:109], 0, v[0:1]
	global_load_dwordx4 v[100:103], v[108:109], off
.Lpf1_topP:
	s_ashr_i32 s14, s51, 9
	s_ashr_i32 s15, s14, 31
	s_and_b32 s52, s51, 0x1e0
	s_lshl_b64 s[46:47], s[14:15], 22
	s_add_u32 s46, s48, s46
	s_addc_u32 s47, s49, s47
	s_and_b32 s15, s50, 0x7c0
	s_lshl_b32 s0, s52, 2
	v_readlane_b32 s81, v253, 50
	v_readlane_b32 s80, v253, 7
	s_add_i32 s81, s51, s81
	s_add_i32 s80, s50, s80
	s_cmpk_gt_i32 s81, 0xfff
	s_cbranch_scc1 .Lpf1_nopfP
	s_mov_b32 s75, s1
	s_ashr_i32 s76, s81, 9
	s_ashr_i32 s77, s76, 31
	s_and_b32 s82, s81, 0x1e0
	s_lshl_b64 s[78:79], s[76:77], 22
	s_add_u32 s78, s48, s78
	s_addc_u32 s79, s49, s79
	s_and_b32 s77, s80, 0x7c0
	v_add_u32_e32 v108, s77, v11
	v_ashrrev_i32_e32 v109, 31, v108
	v_lshlrev_b64 v[108:109], 11, v[108:109]
	v_lshl_add_u64 v[108:109], s[78:79], 0, v[108:109]
	s_lshl_b32 s74, s82, 2
	v_lshl_add_u64 v[108:109], v[108:109], 0, s[74:75]
	v_lshl_add_u64 v[108:109], v[108:109], 0, v[0:1]
	global_load_dwordx4 v[104:107], v[108:109], off
	s_waitcnt vmcnt(1)
	s_branch .Lpf1_goP

.Lpf1_goP:
	v_cvt_pk_bf16_f32 v4, v100, s0
	v_cvt_pk_bf16_f32 v5, v101, s0
	v_cvt_pk_bf16_f32 v6, v102, s0
	v_cvt_pk_bf16_f32 v7, v103, s0
	ds_write_b16 v12, v4
	ds_write_b16 v12, v5 offset:144
	ds_write_b16 v12, v6 offset:288
	ds_write_b16 v12, v7 offset:432
	s_waitcnt lgkmcnt(0)
	s_barrier
	s_and_saveexec_b64 s[46:47], s[4:5]
	s_cbranch_execz .Lpf1_latchP
	s_mul_hi_i32 s0, s14, 0x210000
	s_mul_i32 s14, s14, 0x210000
	s_add_u32 s54, s24, s14
	s_addc_u32 s55, s25, s0
	ds_read_b128 v[4:7], v14
	v_add_u32_e32 v10, s52, v11
	v_mov_b64_e32 v[8:9], s[54:55]
	s_movk_i32 s0, 0x1080
	v_mad_i64_i32 v[8:9], s[52:53], v10, s0, v[8:9]
	v_or_b32_e32 v10, s15, v13
	s_movk_i32 s0, 0x7f0
	v_and_or_b32 v15, v10, s0, v2
	v_lshlrev_b32_e32 v16, 1, v15
	v_mov_b32_e32 v17, v1
	v_lshl_add_u64 v[16:17], v[8:9], 0, v[16:17]
	s_waitcnt lgkmcnt(0)
	global_store_dwordx2 v[16:17], v[4:5], off
	v_or_b32_e32 v4, v10, v3
	v_lshlrev_b32_e32 v4, 1, v4
	v_mov_b32_e32 v5, v1
	v_lshl_add_u64 v[4:5], v[8:9], 0, v[4:5]
	global_store_dwordx2 v[4:5], v[6:7], off
.Lpf1_latchP:
	s_or_b64 exec, exec, s[46:47]
	s_mov_b32 s51, s81
	s_mov_b32 s50, s80
	s_cmpk_gt_i32 s51, 0xfff
	s_barrier
	v_readlane_b32 s15, v253, 51
	s_cbranch_scc1 .LBB0_775
.Lpf1_topQ:
	s_ashr_i32 s14, s51, 9
	s_ashr_i32 s15, s14, 31
	s_and_b32 s52, s51, 0x1e0
	s_lshl_b64 s[46:47], s[14:15], 22
	s_add_u32 s46, s48, s46
	s_addc_u32 s47, s49, s47
	s_and_b32 s15, s50, 0x7c0
	s_lshl_b32 s0, s52, 2
	v_readlane_b32 s81, v253, 50
	v_readlane_b32 s80, v253, 7
	s_add_i32 s81, s51, s81
	s_add_i32 s80, s50, s80
	s_cmpk_gt_i32 s81, 0xfff
	s_cbranch_scc1 .Lpf1_nopfQ
	s_mov_b32 s75, s1
	s_ashr_i32 s76, s81, 9
	s_ashr_i32 s77, s76, 31
	s_and_b32 s82, s81, 0x1e0
	s_lshl_b64 s[78:79], s[76:77], 22
	s_add_u32 s78, s48, s78
	s_addc_u32 s79, s49, s79
	s_and_b32 s77, s80, 0x7c0
	v_add_u32_e32 v108, s77, v11
	v_ashrrev_i32_e32 v109, 31, v108
	v_lshlrev_b64 v[108:109], 11, v[108:109]
	v_lshl_add_u64 v[108:109], s[78:79], 0, v[108:109]
	s_lshl_b32 s74, s82, 2
	v_lshl_add_u64 v[108:109], v[108:109], 0, s[74:75]
	v_lshl_add_u64 v[108:109], v[108:109], 0, v[0:1]
	global_load_dwordx4 v[100:103], v[108:109], off
	s_waitcnt vmcnt(1)
	s_branch .Lpf1_goQ

.Lpf1_goQ:
	v_cvt_pk_bf16_f32 v4, v104, s0
	v_cvt_pk_bf16_f32 v5, v105, s0
	v_cvt_pk_bf16_f32 v6, v106, s0
	v_cvt_pk_bf16_f32 v7, v107, s0
	ds_write_b16 v12, v4
	ds_write_b16 v12, v5 offset:144
	ds_write_b16 v12, v6 offset:288
	ds_write_b16 v12, v7 offset:432
	s_waitcnt lgkmcnt(0)
	s_barrier
	s_and_saveexec_b64 s[46:47], s[4:5]
	s_cbranch_execz .Lpf1_latchQ
	s_mul_hi_i32 s0, s14, 0x210000
	s_mul_i32 s14, s14, 0x210000
	s_add_u32 s54, s24, s14
	s_addc_u32 s55, s25, s0
	ds_read_b128 v[4:7], v14
	v_add_u32_e32 v10, s52, v11
	v_mov_b64_e32 v[8:9], s[54:55]
	s_movk_i32 s0, 0x1080
	v_mad_i64_i32 v[8:9], s[52:53], v10, s0, v[8:9]
	v_or_b32_e32 v10, s15, v13
	s_movk_i32 s0, 0x7f0
	v_and_or_b32 v15, v10, s0, v2
	v_lshlrev_b32_e32 v16, 1, v15
	v_mov_b32_e32 v17, v1
	v_lshl_add_u64 v[16:17], v[8:9], 0, v[16:17]
	s_waitcnt lgkmcnt(0)
	global_store_dwordx2 v[16:17], v[4:5], off
	v_or_b32_e32 v4, v10, v3
	v_lshlrev_b32_e32 v4, 1, v4
	v_mov_b32_e32 v5, v1
	v_lshl_add_u64 v[4:5], v[8:9], 0, v[4:5]
	global_store_dwordx2 v[4:5], v[6:7], off
.Lpf1_latchQ:
	s_or_b64 exec, exec, s[46:47]
	s_mov_b32 s51, s81
	s_mov_b32 s50, s80
	s_cmpk_gt_i32 s51, 0xfff
	s_barrier
	v_readlane_b32 s15, v253, 51
	s_cbranch_scc1 .LBB0_775
	s_branch .Lpf1_topP
